# v105 + next-group global loads of the two register-staged projection loops issued right after the ds_writes (above lgkmcnt(0)+barrier / MFMA tail)
# baseline (speedup 1.0000x reference)
.Lrs_t1:
	s_waitcnt vmcnt(4)
	ds_write_b128 v80, v[2:5]
	ds_write_b128 v80, v[14:17] offset:8192
	ds_write_b128 v80, v[10:13] offset:32768
	ds_write_b128 v80, v[26:29] offset:40960
	s_cbranch_vccnz .LBB0_484
	s_nop 7
	v_add_co_u32_e32 v10, vcc, 0x80000, v76
	global_load_dwordx4 v[2:5], v[76:77], off offset:256
	s_nop 0
	v_addc_co_u32_e32 v11, vcc, 0, v77, vcc
	v_add_co_u32_e32 v26, vcc, 0x80000, v72
	global_load_dwordx4 v[14:17], v[10:11], off offset:256
	s_nop 0
	global_load_dwordx4 v[10:13], v[74:75], off offset:256
	v_addc_co_u32_e32 v27, vcc, 0, v73, vcc
	global_load_dwordx4 v[26:29], v[26:27], off offset:256
.LBB0_484:
	s_waitcnt lgkmcnt(0)
	s_barrier
	ds_read_b128 v[88:91], v84 offset:32768
	ds_read_b128 v[92:95], v84 offset:34816
	ds_read_b128 v[96:99], v83
	ds_read_b128 v[100:103], v83 offset:2048
	s_cmp_gt_u32 s5, 28
	s_waitcnt lgkmcnt(1)
	v_mfma_f32_16x16x32_bf16 v[58:61], v[88:91], v[96:99], v[58:61]
	v_mfma_f32_16x16x32_bf16 v[54:57], v[92:95], v[96:99], v[54:57]
	s_waitcnt lgkmcnt(0)
	v_mfma_f32_16x16x32_bf16 v[50:53], v[88:91], v[100:103], v[50:53]
	v_mfma_f32_16x16x32_bf16 v[46:49], v[92:95], v[100:103], v[46:49]
	ds_read_b128 v[96:99], v83 offset:4096
	ds_read_b128 v[100:103], v83 offset:6144
	s_waitcnt lgkmcnt(1)
	v_mfma_f32_16x16x32_bf16 v[104:107], v[88:91], v[96:99], v[38:41]
	s_waitcnt lgkmcnt(0)
	v_mfma_f32_16x16x32_bf16 v[62:65], v[88:91], v[100:103], v[62:65]
	ds_read_b128 v[88:91], v86 offset:32768
	v_mfma_f32_16x16x32_bf16 v[96:99], v[92:95], v[96:99], v[34:37]
	v_mfma_f32_16x16x32_bf16 v[92:95], v[92:95], v[100:103], v[42:45]
	ds_read_b128 v[100:103], v86 offset:34816
	ds_read_b128 v[38:41], v85
	ds_read_b128 v[108:111], v85 offset:2048
	s_waitcnt lgkmcnt(1)
	v_mfma_f32_16x16x32_bf16 v[34:37], v[88:91], v[38:41], v[58:61]
	v_mfma_f32_16x16x32_bf16 v[38:41], v[100:103], v[38:41], v[54:57]
	s_nop 2
	ds_read_b128 v[54:57], v85 offset:4096
	ds_read_b128 v[58:61], v85 offset:6144
	s_cbranch_scc0 .Lrs_m1
	s_waitcnt vmcnt(0)
.Lrs_m1:
	s_waitcnt vmcnt(4)
	ds_write_b128 v80, v[6:9] offset:16384
	ds_write_b128 v80, v[22:25] offset:24576
	ds_write_b128 v80, v[18:21] offset:49152
	ds_write_b128 v80, v[30:33] offset:57344
	s_cbranch_scc1 .Lrs_b1
	s_nop 7
	v_add_co_u32_e32 v18, vcc, 0x80000, v76
	global_load_dwordx4 v[6:9], v[76:77], off offset:384
	s_nop 0
	v_addc_co_u32_e32 v19, vcc, 0, v77, vcc
	v_add_co_u32_e32 v30, vcc, 0x80000, v72
	global_load_dwordx4 v[22:25], v[18:19], off offset:384
	s_nop 0
	global_load_dwordx4 v[18:21], v[74:75], off offset:384
	v_addc_co_u32_e32 v31, vcc, 0, v73, vcc
	global_load_dwordx4 v[30:33], v[30:31], off offset:384
.Lrs_b1:
	s_waitcnt lgkmcnt(6)
	v_mfma_f32_16x16x32_bf16 v[42:45], v[88:91], v[108:111], v[50:53]
	s_waitcnt lgkmcnt(0)
	s_barrier
	v_mfma_f32_16x16x32_bf16 v[46:49], v[100:103], v[108:111], v[46:49]
	v_mfma_f32_16x16x32_bf16 v[50:53], v[88:91], v[54:57], v[104:107]
	v_mfma_f32_16x16x32_bf16 v[54:57], v[100:103], v[54:57], v[96:99]
	v_mfma_f32_16x16x32_bf16 v[62:65], v[88:91], v[58:61], v[62:65]
	v_mfma_f32_16x16x32_bf16 v[58:61], v[100:103], v[58:61], v[92:95]
	s_branch .LBB0_481

.Lrs_t2:
	s_waitcnt vmcnt(4)
	ds_write_b128 v84, v[18:21]
	ds_write_b128 v84, v[22:25] offset:8192
	ds_write_b128 v84, v[34:37] offset:32768
	ds_write_b128 v84, v[46:49] offset:40960
	s_cbranch_vccnz .LBB0_490
	s_nop 7
	v_add_co_u32_e32 v18, vcc, 0x1000, v76
	s_nop 1
	v_addc_co_u32_e32 v19, vcc, 0, v77, vcc
	v_add_co_u32_e32 v22, vcc, 0x81000, v76
	s_nop 1
	v_addc_co_u32_e32 v23, vcc, 0, v77, vcc
	v_add_co_u32_e32 v34, vcc, 0x1000, v74
	global_load_dwordx4 v[18:21], v[18:19], off offset:256
	s_nop 0
	global_load_dwordx4 v[22:25], v[22:23], off offset:256
	v_addc_co_u32_e32 v35, vcc, 0, v75, vcc
	v_add_co_u32_e32 v46, vcc, 0x81000, v72
	global_load_dwordx4 v[34:37], v[34:35], off offset:256
	s_nop 0
	v_addc_co_u32_e32 v47, vcc, 0, v73, vcc
	global_load_dwordx4 v[46:49], v[46:47], off offset:256
.LBB0_490:
	s_waitcnt lgkmcnt(0)
	s_barrier
	ds_read_b128 v[90:93], v86 offset:32768
	ds_read_b128 v[94:97], v86 offset:34816
	ds_read_b128 v[98:101], v85
	ds_read_b128 v[102:105], v85 offset:2048
	s_cmp_gt_u32 s5, 28
	s_waitcnt lgkmcnt(1)
	v_mfma_f32_16x16x32_bf16 v[62:65], v[90:93], v[98:101], v[62:65]
	v_mfma_f32_16x16x32_bf16 v[58:61], v[94:97], v[98:101], v[58:61]
	s_waitcnt lgkmcnt(0)
	v_mfma_f32_16x16x32_bf16 v[54:57], v[90:93], v[102:105], v[54:57]
	v_mfma_f32_16x16x32_bf16 v[42:45], v[94:97], v[102:105], v[42:45]
	ds_read_b128 v[98:101], v85 offset:4096
	ds_read_b128 v[102:105], v85 offset:6144
	ds_read_b128 v[106:109], v88 offset:32768
	s_waitcnt lgkmcnt(2)
	v_mfma_f32_16x16x32_bf16 v[14:17], v[90:93], v[98:101], v[14:17]
	v_mfma_f32_16x16x32_bf16 v[98:101], v[94:97], v[98:101], v[10:13]
	s_waitcnt lgkmcnt(1)
	v_mfma_f32_16x16x32_bf16 v[90:93], v[90:93], v[102:105], v[6:9]
	v_mfma_f32_16x16x32_bf16 v[2:5], v[94:97], v[102:105], v[2:5]
	ds_read_b128 v[94:97], v88 offset:34816
	s_nop 0
	ds_read_b128 v[6:9], v87
	ds_read_b128 v[10:13], v87 offset:2048
	s_waitcnt lgkmcnt(1)
	v_mfma_f32_16x16x32_bf16 v[62:65], v[106:109], v[6:9], v[62:65]
	v_mfma_f32_16x16x32_bf16 v[58:61], v[94:97], v[6:9], v[58:61]
	s_waitcnt lgkmcnt(0)
	v_mfma_f32_16x16x32_bf16 v[6:9], v[106:109], v[10:13], v[54:57]
	s_nop 2
	ds_read_b128 v[54:57], v87 offset:4096
	ds_read_b128 v[102:105], v87 offset:6144
	s_cbranch_scc0 .Lrs_m2
	s_waitcnt vmcnt(0)
.Lrs_m2:
	s_waitcnt vmcnt(4)
	ds_write_b128 v84, v[26:29] offset:16384
	ds_write_b128 v84, v[30:33] offset:24576
	ds_write_b128 v84, v[38:41] offset:49152
	ds_write_b128 v84, v[50:53] offset:57344
	s_cbranch_scc1 .Lrs_b2
	s_nop 7
	v_add_co_u32_e32 v26, vcc, 0x1000, v76
	s_nop 1
	v_addc_co_u32_e32 v27, vcc, 0, v77, vcc
	v_add_co_u32_e32 v30, vcc, 0x81000, v76
	s_nop 1
	v_addc_co_u32_e32 v31, vcc, 0, v77, vcc
	v_add_co_u32_e32 v38, vcc, 0x1000, v74
	global_load_dwordx4 v[26:29], v[26:27], off offset:384
	s_nop 0
	global_load_dwordx4 v[30:33], v[30:31], off offset:384
	v_addc_co_u32_e32 v39, vcc, 0, v75, vcc
	v_add_co_u32_e32 v50, vcc, 0x81000, v72
	global_load_dwordx4 v[38:41], v[38:39], off offset:384
	s_nop 0
	v_addc_co_u32_e32 v51, vcc, 0, v73, vcc
	global_load_dwordx4 v[50:53], v[50:51], off offset:384
.Lrs_b2:
	v_mfma_f32_16x16x32_bf16 v[10:13], v[94:97], v[10:13], v[42:45]
	s_waitcnt lgkmcnt(0)
	s_barrier
	v_mfma_f32_16x16x32_bf16 v[42:45], v[106:109], v[54:57], v[14:17]
	v_mfma_f32_16x16x32_bf16 v[54:57], v[94:97], v[54:57], v[98:101]
	v_mfma_f32_16x16x32_bf16 v[14:17], v[106:109], v[102:105], v[90:93]
	v_mfma_f32_16x16x32_bf16 v[2:5], v[94:97], v[102:105], v[2:5]
	s_branch .LBB0_487
